# v3 + attention tile body rewritten by hand: both score blocks live, each V fragment read once and used by both components' P.V MFMAs (32 fewer LDS transpose reads per tile)
# speedup vs baseline: 1.0215x; 1.0130x over previous
.LBB0_121:
	v_and_b32_e32 v129, 31, v128
	v_bfe_u32 v130, v128, 5, 1
	s_mul_i32 s8, s20, 0x4400
	v_bfe_u32 v131, v128, 2, 2
	v_and_b32_e32 v132, 16, v128
	v_lshlrev_b32_e32 v128, 2, v128
	s_add_i32 s8, s8, 0
	v_mul_u32_u24_e32 v136, 0x110, v129
	v_lshlrev_b32_e32 v137, 4, v130
	v_and_or_b32 v128, v128, 12, v132
	v_lshl_or_b32 v129, v130, 2, v131
	v_add3_u32 v164, s8, v136, v137
	v_mul_u32_u24_e32 v162, 0x140, v129
	v_lshlrev_b32_e32 v163, 1, v128
	v_add3_u32 v165, s28, v136, v137
	s_add_i32 s11, s11, 1
	s_mulk_i32 s20, 0xc00
	s_add_i32 s9, s8, s20
	v_add3_u32 v162, s9, v162, v163
	ds_read_b128 v[128:131], v164
	ds_read_b128 v[132:135], v164 offset:8704
	ds_read_b128 v[136:139], v165
	ds_read_b128 v[176:179], v164 offset:32
	ds_read_b128 v[180:183], v164 offset:8736
	ds_read_b128 v[184:187], v165 offset:32
	s_waitcnt lgkmcnt(3)
	s_setprio 1
	v_mfma_f32_32x32x16_bf16 v[144:159], v[128:131], v[136:139], 0
	v_mfma_f32_32x32x16_bf16 v[128:143], v[132:135], v[136:139], 0
	s_setprio 0
	ds_read_b128 v[188:191], v164 offset:64
	ds_read_b128 v[192:195], v164 offset:8768
	ds_read_b128 v[196:199], v165 offset:64
	s_waitcnt lgkmcnt(3)
	s_setprio 1
	v_mfma_f32_32x32x16_bf16 v[144:159], v[176:179], v[184:187], v[144:159]
	v_mfma_f32_32x32x16_bf16 v[128:143], v[180:183], v[184:187], v[128:143]
	s_setprio 0
	ds_read_b128 v[200:203], v164 offset:96
	ds_read_b128 v[204:207], v164 offset:8800
	ds_read_b128 v[208:211], v165 offset:96
	s_waitcnt lgkmcnt(3)
	s_setprio 1
	v_mfma_f32_32x32x16_bf16 v[144:159], v[188:191], v[196:199], v[144:159]
	v_mfma_f32_32x32x16_bf16 v[128:143], v[192:195], v[196:199], v[128:143]
	s_setprio 0
	s_waitcnt lgkmcnt(0)
	s_setprio 1
	v_mfma_f32_32x32x16_bf16 v[144:159], v[200:203], v[208:211], v[144:159]
	v_mfma_f32_32x32x16_bf16 v[128:143], v[204:207], v[208:211], v[128:143]
	s_setprio 0
	ds_read_b128 v[208:211], v164 offset:128
	ds_read_b128 v[212:215], v164 offset:8832
	ds_read_b128 v[250:253], v165 offset:128
	ds_read_b128 v[166:169], v164 offset:160
	ds_read_b128 v[232:235], v164 offset:8864
	ds_read_b128 v[246:249], v165 offset:160
	ds_read_b64_tr_b16 v[224:225], v162 offset:34816
	ds_read_b64_tr_b16 v[226:227], v162 offset:37376
	ds_read_b64_tr_b16 v[228:229], v162 offset:34880
	ds_read_b64_tr_b16 v[230:231], v162 offset:37440
	s_waitcnt lgkmcnt(7)
	s_setprio 1
	v_mfma_f32_32x32x16_bf16 v[176:191], v[208:211], v[250:253], 0
	v_mfma_f32_32x32x16_bf16 v[192:207], v[212:215], v[250:253], 0
	s_setprio 0
	ds_read_b128 v[208:211], v164 offset:192
	ds_read_b128 v[212:215], v164 offset:8896
	ds_read_b128 v[250:253], v165 offset:192
	v_exp_f32_e32 v144, v144
	v_exp_f32_e32 v145, v145
	s_nop 0
	v_add_f32_e32 v170, v144, v145
	v_cvt_pk_bf16_f32 v144, v144, v145
	s_waitcnt lgkmcnt(7)
	s_setprio 1
	v_mfma_f32_32x32x16_bf16 v[176:191], v[166:169], v[246:249], v[176:191]
	v_mfma_f32_32x32x16_bf16 v[192:207], v[232:235], v[246:249], v[192:207]
	s_setprio 0
	ds_read_b128 v[166:169], v164 offset:224
	ds_read_b128 v[232:235], v164 offset:8928
	ds_read_b128 v[246:249], v165 offset:224
	v_exp_f32_e32 v146, v146
	v_exp_f32_e32 v147, v147
	s_nop 0
	v_add_f32_e32 v171, v146, v147
	v_cvt_pk_bf16_f32 v145, v146, v147
	s_waitcnt lgkmcnt(3)
	s_setprio 1
	v_mfma_f32_32x32x16_bf16 v[176:191], v[208:211], v[250:253], v[176:191]
	v_mfma_f32_32x32x16_bf16 v[192:207], v[212:215], v[250:253], v[192:207]
	s_setprio 0
	v_exp_f32_e32 v148, v148
	v_exp_f32_e32 v149, v149
	s_nop 0
	v_add_f32_e32 v172, v148, v149
	v_cvt_pk_bf16_f32 v146, v148, v149
	s_waitcnt lgkmcnt(0)
	s_setprio 1
	v_mfma_f32_32x32x16_bf16 v[176:191], v[166:169], v[246:249], v[176:191]
	v_mfma_f32_32x32x16_bf16 v[192:207], v[232:235], v[246:249], v[192:207]
	s_setprio 0
	ds_read_b64_tr_b16 v[232:233], v162 offset:34944
	ds_read_b64_tr_b16 v[234:235], v162 offset:37504
	ds_read_b64_tr_b16 v[246:247], v162 offset:35008
	ds_read_b64_tr_b16 v[248:249], v162 offset:37568
	v_exp_f32_e32 v150, v150
	v_exp_f32_e32 v151, v151
	s_nop 0
	v_add_f32_e32 v173, v150, v151
	v_cvt_pk_bf16_f32 v147, v150, v151
	v_add_f32_e32 v170, v170, v171
	v_add_f32_e32 v172, v172, v173
	v_add_f32_e32 v170, v170, v172
	v_add_f32_e32 v174, v174, v170
	s_waitcnt lgkmcnt(0)
	s_setprio 1
	v_mfma_f32_32x32x16_bf16 v[112:127], v[144:147], v[224:227], v[112:127]
	v_exp_f32_e32 v176, v176
	v_exp_f32_e32 v177, v177
	ds_read_b64_tr_b16 v[208:209], v162 offset:39936
	ds_read_b64_tr_b16 v[210:211], v162 offset:42496
	v_add_f32_e32 v170, v176, v177
	v_cvt_pk_bf16_f32 v176, v176, v177
	v_mfma_f32_32x32x16_bf16 v[96:111], v[144:147], v[228:231], v[96:111]
	v_exp_f32_e32 v178, v178
	v_exp_f32_e32 v179, v179
	s_nop 0
	v_add_f32_e32 v171, v178, v179
	v_cvt_pk_bf16_f32 v177, v178, v179
	v_mfma_f32_32x32x16_bf16 v[80:95], v[144:147], v[232:235], v[80:95]
	v_exp_f32_e32 v180, v180
	v_exp_f32_e32 v181, v181
	ds_read_b64_tr_b16 v[212:213], v162 offset:40000
	ds_read_b64_tr_b16 v[214:215], v162 offset:42560
	v_add_f32_e32 v172, v180, v181
	v_cvt_pk_bf16_f32 v178, v180, v181
	v_mfma_f32_32x32x16_bf16 v[64:79], v[144:147], v[246:249], v[64:79]
	v_exp_f32_e32 v182, v182
	v_exp_f32_e32 v183, v183
	s_nop 0
	v_add_f32_e32 v173, v182, v183
	v_cvt_pk_bf16_f32 v179, v182, v183
	s_setprio 0
	v_add_f32_e32 v170, v170, v171
	v_add_f32_e32 v172, v172, v173
	v_add_f32_e32 v170, v170, v172
	v_add_f32_e32 v175, v175, v170
	s_waitcnt lgkmcnt(4)
	s_setprio 1
	v_mfma_f32_32x32x16_bf16 v[48:63], v[176:179], v[224:227], v[48:63]
	v_exp_f32_e32 v152, v152
	v_exp_f32_e32 v153, v153
	ds_read_b64_tr_b16 v[250:251], v162 offset:40064
	ds_read_b64_tr_b16 v[252:253], v162 offset:42624
	v_add_f32_e32 v170, v152, v153
	v_cvt_pk_bf16_f32 v152, v152, v153
	v_mfma_f32_32x32x16_bf16 v[32:47], v[176:179], v[228:231], v[32:47]
	v_exp_f32_e32 v154, v154
	v_exp_f32_e32 v155, v155
	s_nop 0
	v_add_f32_e32 v171, v154, v155
	v_cvt_pk_bf16_f32 v153, v154, v155
	v_mfma_f32_32x32x16_bf16 v[16:31], v[176:179], v[232:235], v[16:31]
	v_exp_f32_e32 v156, v156
	v_exp_f32_e32 v157, v157
	ds_read_b64_tr_b16 v[166:167], v162 offset:40128
	ds_read_b64_tr_b16 v[168:169], v162 offset:42688
	v_add_f32_e32 v172, v156, v157
	v_cvt_pk_bf16_f32 v154, v156, v157
	v_mfma_f32_32x32x16_bf16 v[0:15], v[176:179], v[246:249], v[0:15]
	v_exp_f32_e32 v158, v158
	v_exp_f32_e32 v159, v159
	s_nop 0
	v_add_f32_e32 v173, v158, v159
	v_cvt_pk_bf16_f32 v155, v158, v159
	s_setprio 0
	v_add_f32_e32 v170, v170, v171
	v_add_f32_e32 v172, v172, v173
	v_add_f32_e32 v170, v170, v172
	v_add_f32_e32 v174, v174, v170
	s_waitcnt lgkmcnt(0)
	s_setprio 1
	v_mfma_f32_32x32x16_bf16 v[112:127], v[152:155], v[208:211], v[112:127]
	v_exp_f32_e32 v184, v184
	v_exp_f32_e32 v185, v185
	ds_read_b64_tr_b16 v[224:225], v162 offset:45056
	ds_read_b64_tr_b16 v[226:227], v162 offset:47616
	v_add_f32_e32 v170, v184, v185
	v_cvt_pk_bf16_f32 v184, v184, v185
	v_mfma_f32_32x32x16_bf16 v[96:111], v[152:155], v[212:215], v[96:111]
	v_exp_f32_e32 v186, v186
	v_exp_f32_e32 v187, v187
	s_nop 0
	v_add_f32_e32 v171, v186, v187
	v_cvt_pk_bf16_f32 v185, v186, v187
	v_mfma_f32_32x32x16_bf16 v[80:95], v[152:155], v[250:253], v[80:95]
	v_exp_f32_e32 v188, v188
	v_exp_f32_e32 v189, v189
	ds_read_b64_tr_b16 v[228:229], v162 offset:45120
	ds_read_b64_tr_b16 v[230:231], v162 offset:47680
	v_add_f32_e32 v172, v188, v189
	v_cvt_pk_bf16_f32 v186, v188, v189
	v_mfma_f32_32x32x16_bf16 v[64:79], v[152:155], v[166:169], v[64:79]
	v_exp_f32_e32 v190, v190
	v_exp_f32_e32 v191, v191
	s_nop 0
	v_add_f32_e32 v173, v190, v191
	v_cvt_pk_bf16_f32 v187, v190, v191
	s_setprio 0
	v_add_f32_e32 v170, v170, v171
	v_add_f32_e32 v172, v172, v173
	v_add_f32_e32 v170, v170, v172
	v_add_f32_e32 v175, v175, v170
	s_waitcnt lgkmcnt(4)
	s_setprio 1
	v_mfma_f32_32x32x16_bf16 v[48:63], v[184:187], v[208:211], v[48:63]
	v_exp_f32_e32 v128, v128
	v_exp_f32_e32 v129, v129
	ds_read_b64_tr_b16 v[232:233], v162 offset:45184
	ds_read_b64_tr_b16 v[234:235], v162 offset:47744
	v_add_f32_e32 v170, v128, v129
	v_cvt_pk_bf16_f32 v128, v128, v129
	v_mfma_f32_32x32x16_bf16 v[32:47], v[184:187], v[212:215], v[32:47]
	v_exp_f32_e32 v130, v130
	v_exp_f32_e32 v131, v131
	s_nop 0
	v_add_f32_e32 v171, v130, v131
	v_cvt_pk_bf16_f32 v129, v130, v131
	v_mfma_f32_32x32x16_bf16 v[16:31], v[184:187], v[250:253], v[16:31]
	v_exp_f32_e32 v132, v132
	v_exp_f32_e32 v133, v133
	ds_read_b64_tr_b16 v[246:247], v162 offset:45248
	ds_read_b64_tr_b16 v[248:249], v162 offset:47808
	v_add_f32_e32 v172, v132, v133
	v_cvt_pk_bf16_f32 v130, v132, v133
	v_mfma_f32_32x32x16_bf16 v[0:15], v[184:187], v[166:169], v[0:15]
	v_exp_f32_e32 v134, v134
	v_exp_f32_e32 v135, v135
	s_nop 0
	v_add_f32_e32 v173, v134, v135
	v_cvt_pk_bf16_f32 v131, v134, v135
	s_setprio 0
	v_add_f32_e32 v170, v170, v171
	v_add_f32_e32 v172, v172, v173
	v_add_f32_e32 v170, v170, v172
	v_add_f32_e32 v174, v174, v170
	s_waitcnt lgkmcnt(0)
	s_setprio 1
	v_mfma_f32_32x32x16_bf16 v[112:127], v[128:131], v[224:227], v[112:127]
	v_exp_f32_e32 v192, v192
	v_exp_f32_e32 v193, v193
	ds_read_b64_tr_b16 v[208:209], v162 offset:50176
	ds_read_b64_tr_b16 v[210:211], v162 offset:52736
	v_add_f32_e32 v170, v192, v193
	v_cvt_pk_bf16_f32 v192, v192, v193
	v_mfma_f32_32x32x16_bf16 v[96:111], v[128:131], v[228:231], v[96:111]
	v_exp_f32_e32 v194, v194
	v_exp_f32_e32 v195, v195
	s_nop 0
	v_add_f32_e32 v171, v194, v195
	v_cvt_pk_bf16_f32 v193, v194, v195
	v_mfma_f32_32x32x16_bf16 v[80:95], v[128:131], v[232:235], v[80:95]
	v_exp_f32_e32 v196, v196
	v_exp_f32_e32 v197, v197
	ds_read_b64_tr_b16 v[212:213], v162 offset:50240
	ds_read_b64_tr_b16 v[214:215], v162 offset:52800
	v_add_f32_e32 v172, v196, v197
	v_cvt_pk_bf16_f32 v194, v196, v197
	v_mfma_f32_32x32x16_bf16 v[64:79], v[128:131], v[246:249], v[64:79]
	v_exp_f32_e32 v198, v198
	v_exp_f32_e32 v199, v199
	s_nop 0
	v_add_f32_e32 v173, v198, v199
	v_cvt_pk_bf16_f32 v195, v198, v199
	s_setprio 0
	v_add_f32_e32 v170, v170, v171
	v_add_f32_e32 v172, v172, v173
	v_add_f32_e32 v170, v170, v172
	v_add_f32_e32 v175, v175, v170
	s_waitcnt lgkmcnt(4)
	s_setprio 1
	v_mfma_f32_32x32x16_bf16 v[48:63], v[192:195], v[224:227], v[48:63]
	v_exp_f32_e32 v136, v136
	v_exp_f32_e32 v137, v137
	ds_read_b64_tr_b16 v[250:251], v162 offset:50304
	ds_read_b64_tr_b16 v[252:253], v162 offset:52864
	v_add_f32_e32 v170, v136, v137
	v_cvt_pk_bf16_f32 v136, v136, v137
	v_mfma_f32_32x32x16_bf16 v[32:47], v[192:195], v[228:231], v[32:47]
	v_exp_f32_e32 v138, v138
	v_exp_f32_e32 v139, v139
	s_nop 0
	v_add_f32_e32 v171, v138, v139
	v_cvt_pk_bf16_f32 v137, v138, v139
	v_mfma_f32_32x32x16_bf16 v[16:31], v[192:195], v[232:235], v[16:31]
	v_exp_f32_e32 v140, v140
	v_exp_f32_e32 v141, v141
	ds_read_b64_tr_b16 v[166:167], v162 offset:50368
	ds_read_b64_tr_b16 v[168:169], v162 offset:52928
	v_add_f32_e32 v172, v140, v141
	v_cvt_pk_bf16_f32 v138, v140, v141
	v_mfma_f32_32x32x16_bf16 v[0:15], v[192:195], v[246:249], v[0:15]
	v_exp_f32_e32 v142, v142
	v_exp_f32_e32 v143, v143
	s_nop 0
	v_add_f32_e32 v173, v142, v143
	v_cvt_pk_bf16_f32 v139, v142, v143
	s_setprio 0
	v_add_f32_e32 v170, v170, v171
	v_add_f32_e32 v172, v172, v173
	v_add_f32_e32 v170, v170, v172
	v_add_f32_e32 v174, v174, v170
	s_waitcnt lgkmcnt(0)
	s_setprio 1
	v_mfma_f32_32x32x16_bf16 v[112:127], v[136:139], v[208:211], v[112:127]
	v_exp_f32_e32 v200, v200
	v_exp_f32_e32 v201, v201
	s_nop 0
	v_add_f32_e32 v170, v200, v201
	v_cvt_pk_bf16_f32 v200, v200, v201
	v_mfma_f32_32x32x16_bf16 v[96:111], v[136:139], v[212:215], v[96:111]
	v_exp_f32_e32 v202, v202
	v_exp_f32_e32 v203, v203
	s_nop 0
	v_add_f32_e32 v171, v202, v203
	v_cvt_pk_bf16_f32 v201, v202, v203
	v_mfma_f32_32x32x16_bf16 v[80:95], v[136:139], v[250:253], v[80:95]
	v_exp_f32_e32 v204, v204
	v_exp_f32_e32 v205, v205
	s_nop 0
	v_add_f32_e32 v172, v204, v205
	v_cvt_pk_bf16_f32 v202, v204, v205
	v_mfma_f32_32x32x16_bf16 v[64:79], v[136:139], v[166:169], v[64:79]
	v_exp_f32_e32 v206, v206
	v_exp_f32_e32 v207, v207
	s_nop 0
	v_add_f32_e32 v173, v206, v207
	v_cvt_pk_bf16_f32 v203, v206, v207
	s_setprio 0
	v_add_f32_e32 v170, v170, v171
	v_add_f32_e32 v172, v172, v173
	v_add_f32_e32 v170, v170, v172
	v_add_f32_e32 v175, v175, v170
	s_waitcnt lgkmcnt(0)
	s_setprio 1
	v_mfma_f32_32x32x16_bf16 v[48:63], v[200:203], v[208:211], v[48:63]
	v_mfma_f32_32x32x16_bf16 v[32:47], v[200:203], v[212:215], v[32:47]
	v_mfma_f32_32x32x16_bf16 v[16:31], v[200:203], v[250:253], v[16:31]
	v_mfma_f32_32x32x16_bf16 v[0:15], v[200:203], v[166:169], v[0:15]
	s_setprio 0
	s_waitcnt vmcnt(0)
	s_add_u32 s6, s6, 0x20000
	s_addc_u32 s7, s7, 0
	s_cmp_eq_u32 s10, s11
	s_barrier
	s_cbranch_scc1 .LBB0_126
